# v062 plus slc loop: next step's list byte and selection-mask word read during the current step and rotated in at the loop bottom (no LDS wait at the step top)
# baseline (speedup 1.0000x reference)
; DI float bf2f(bf16_t v) { return __uint_as_float(((unsigned)v) << 16); }
; DI float sigmoid_f(float x) { return 1.f / (1.f + __expf(-x)); }
; DI void slc_unit(const Params& P, lptr L, int u, int tid, int lane, int wid) {
;     ...
;     int NTS = 0;
; #pragma unroll
;     for (int k = 0; k < 8; ++k) NTS += __popc(un[k]);
;     __syncthreads();
;     bf16x8 qf[4]; load_q(qf, PROJ + row * PROJ_LD + 1024 + head * 64, hi);
;     const float gs = sigmoid_f(bf2f(PROJ[row * PROJ_LD + 1792 + head * 3 + 1]));
;     f32x16 o0, o1;
; #pragma unroll
;     for (int r = 0; r < 16; ++r) { o0[r] = 0.f; o1[r] = 0.f; }
;     RowState rs; rs.mref = 0.f; rs.l = 0.f; rs.seen = false;
;     const bf16_t* kb_ = PROJ + (size_t)(b * SEQ) * PROJ_LD + 1536 + g * 64; const size_t kpitch_ = PROJ_LD;
;     const bf16_t* vb_ = VT + (size_t)((b * 12 + 8 + g) * 64) * VTP; const size_t vpitch_ = VTP;
;     ATT_LOOP_BEGIN(NTS, false, kb_ + (size_t)((int)list[jt] * 64) * PROJ_LD, vb_ + (size_t)((int)list[jt]) * 64, (const float*)nullptr)
;         const int j = (int)list[jt], kv0 = j * 64;
;         const bool sel = (sm[ql * 8 + (j >> 5)] >> (j & 31)) & 1u;
.LBB0_609:
	s_or_b64 exec, exec, s[2:3]
	s_not_b32 s2, s47
	s_lshl_b32 s2, s2, 3
	ds_read_b128 v[2:5], v1 offset:37376
	ds_read_b128 v[6:9], v1 offset:37392
	s_and_b32 s2, s2, 0x3fc0
	v_add_u32_e32 v91, s2, v179
	v_readlane_b32 s2, v251, 58
	v_readlane_b32 s3, v251, 59
	v_add_u32_e32 v90, s50, v91
	s_waitcnt lgkmcnt(1)
	v_bcnt_u32_b32 v10, v4, 0
	v_bcnt_u32_b32 v11, v5, 0
	v_mov_b64_e32 v[4:5], s[2:3]
	s_movk_i32 s2, 0x1080
	v_bcnt_u32_b32 v3, v3, 0
	v_mad_u64_u32 v[4:5], s[2:3], v90, s2, v[4:5]
	v_bcnt_u32_b32 v2, v2, 0
	s_lshl_b32 s82, s51, 1
	s_lshl_b32 s2, s49, 1
	s_mov_b32 s3, s83
	v_add_u32_e32 v2, v3, v2
	s_waitcnt lgkmcnt(0)
	v_bcnt_u32_b32 v12, v6, 0
	v_bcnt_u32_b32 v13, v7, 0
	v_lshl_add_u64 v[6:7], v[4:5], 0, s[82:83]
	v_lshl_add_u64 v[4:5], v[4:5], 0, s[2:3]
	v_add_u32_e32 v2, v2, v10
	s_add_i32 s2, s33, s48
	v_add_u32_e32 v2, v2, v11
	s_mul_i32 s2, s2, 0x202000
	v_add_u32_e32 v2, v2, v12
	s_add_i32 s2, s2, 0x1010000
	v_readlane_b32 s3, v251, 60
	v_bcnt_u32_b32 v8, v8, 0
	v_add_u32_e32 v2, v2, v13
	s_add_u32 s22, s3, s2
	v_readlane_b32 s2, v251, 61
	v_bcnt_u32_b32 v9, v9, 0
	v_mov_b32_e32 v153, v1
	v_add_u32_e32 v2, v2, v8
	s_addc_u32 s23, s2, 0
	s_add_i32 s2, 0, 0x1a104
	v_lshl_add_u64 v[6:7], v[6:7], 0, v[152:153]
	v_add_u32_e32 v99, v2, v9
	v_mov_b32_e32 v2, s2
	s_barrier
	global_load_dwordx4 v[66:69], v[6:7], off offset:2048
	global_load_dwordx4 v[70:73], v[6:7], off offset:2080
	global_load_dwordx4 v[74:77], v[6:7], off offset:2112
	global_load_dwordx4 v[78:81], v[6:7], off offset:2144
	global_load_ushort v98, v[4:5], off offset:3586
	ds_read_u8 v4, v2
	s_mov_b32 s2, 0x42000
	v_mov_b32_e32 v3, v1
	v_mov_b32_e32 v163, v1
	v_mov_b32_e32 v5, v1
	s_waitcnt lgkmcnt(0)
	v_mul_lo_u32 v2, v4, s2
	v_mov_b32_e32 v253, v4
	v_lshl_add_u64 v[2:3], s[0:1], 0, v[2:3]
	v_lshlrev_b32_e32 v4, 7, v4
	v_lshl_add_u64 v[2:3], v[2:3], 0, v[162:163]
	v_lshl_add_u64 v[4:5], s[22:23], 0, v[4:5]
	v_lshl_add_u64 v[2:3], v[2:3], 0, v[0:1]
	v_mov_b32_e32 v161, v1
	global_load_dwordx4 v[82:85], v[2:3], off offset:3072
	v_lshl_add_u64 v[2:3], v[4:5], 0, v[160:161]
	v_lshl_add_u64 v[2:3], v[2:3], 0, v[0:1]
	global_load_dwordx4 v[86:89], v[2:3], off
	v_cmp_eq_u32_e32 vcc, 0, v99
	s_and_b64 vcc, exec, vcc
	s_waitcnt vmcnt(1)
	ds_write_b128 v127, v[82:85]
	s_waitcnt vmcnt(0)
	ds_write_b128 v127, v[86:89] offset:18432
	s_waitcnt lgkmcnt(0)
	s_barrier
	s_cbranch_vccnz .LBB0_623
	v_lshl_add_u64 v[2:3], s[22:23], 0, v[160:161]
	v_mov_b32_e32 v14, v1
	v_mov_b32_e32 v15, v1
	v_lshl_add_u64 v[92:93], v[2:3], 0, v[0:1]
	v_mov_b32_e32 v0, v1
	v_mov_b32_e32 v2, v1
	v_mov_b32_e32 v3, v1
	v_mov_b32_e32 v4, v1
	v_mov_b32_e32 v5, v1
	v_mov_b32_e32 v6, v1
	v_mov_b32_e32 v7, v1
	v_mov_b32_e32 v8, v1
	v_mov_b32_e32 v9, v1
	v_mov_b32_e32 v10, v1
	v_mov_b32_e32 v11, v1
	v_mov_b32_e32 v12, v1
	v_mov_b32_e32 v13, v1
	v_mov_b64_e32 v[32:33], v[14:15]
	v_mov_b64_e32 v[30:31], v[12:13]
	v_mov_b64_e32 v[28:29], v[10:11]
	v_mov_b64_e32 v[26:27], v[8:9]
	v_mov_b64_e32 v[24:25], v[6:7]
	v_mov_b64_e32 v[22:23], v[4:5]
	v_mov_b64_e32 v[20:21], v[2:3]
	v_mov_b64_e32 v[18:19], v[0:1]
	v_mov_b64_e32 v[16:17], v[14:15]
	v_mov_b32_e32 v94, v150
	v_mov_b32_e32 v95, v150
	s_mov_b32 s0, 0
	v_mov_b32_e32 v96, v150
	v_mov_b32_e32 v97, v150
	s_mov_b64 s[22:23], 0
	v_mov_b32_e32 v100, 0
	v_mov_b64_e32 v[14:15], v[12:13]
	v_mov_b64_e32 v[12:13], v[10:11]
	v_mov_b64_e32 v[10:11], v[8:9]
	v_mov_b64_e32 v[8:9], v[6:7]
	v_mov_b64_e32 v[6:7], v[4:5]
	v_mov_b64_e32 v[4:5], v[2:3]
	v_mov_b64_e32 v[2:3], v[0:1]
	v_mov_b32_e32 v101, 0
	v_mov_b32_e32 v0, 0x1a105
	ds_read_u8 v254, v0
	v_lshrrev_b32_e32 v34, 3, v253
	v_and_b32_e32 v34, 28, v34
	v_add_u32_e32 v34, v186, v34
	ds_read_b32 v255, v34
	s_waitcnt lgkmcnt(0)
.LBB0_611:
	s_add_i32 s30, s0, 1
	v_cmp_ge_u32_e64 s[24:25], s30, v99
	v_cmp_lt_u32_e64 s[26:27], s30, v99
	v_lshrrev_b32_e32 v34, 3, v254
	v_and_b32_e32 v34, 28, v34
	v_add_u32_e32 v34, v186, v34
	ds_read_b32 v247, v34
	s_add_i32 s1, s0, 0x1a106
	v_mov_b32_e32 v0, s1
	ds_read_u8 v248, v0
	s_and_b64 vcc, exec, s[24:25]
	s_cbranch_vccnz .LBB0_613
	s_mov_b32 s1, 0x42000
	v_mov_b32_e32 v35, v1
	v_mul_lo_u32 v0, v254, s1
	v_lshlrev_b32_e32 v34, 7, v254
	v_lshl_add_u64 v[36:37], v[156:157], 0, v[0:1]
	v_lshl_add_u64 v[34:35], v[92:93], 0, v[34:35]
	global_load_dwordx4 v[82:85], v[36:37], off offset:3072
	global_load_dwordx4 v[86:89], v[34:35], off
; template <int MODE>
; DI void bias_init(f32x16& s0, f32x16& s1, const TP& tp, float fbm, int hi) {
; #pragma unroll
;     for (int r = 0; r < 16; ++r) {
;         const int kvc = 16 * (r >> 3) + (r & 7);
;         if (MODE == 0) { s0[r] = __builtin_fmaf(-L2E, tp.cs[kvc + 8 * hi], fbm); s1[r] = __builtin_fmaf(-L2E, tp.cs[kvc + 32 + 8 * hi], fbm); }
;         else { s0[r] = __builtin_fmaf(tp.sl, (float)kvc, fbm); s1[r] = __builtin_fmaf(tp.sl, (float)(kvc + 32), fbm); }
;     }
; }
; DI float max3_asm(float a, float b, float c) { float r; asm("v_max3_f32 %0, %1, %2, %3" : "=v"(r) : "v"(a), "v"(b), "v"(c)); return r; }
; template <bool MASK>
; DI float mask_rowmax(f32x16& s0, f32x16& s1, const TP& tp) {
;     if (MASK) {
; #pragma unroll
;         for (int r = 0; r < 16; ++r) {
;             const int kvc = 16 * (r >> 3) + (r & 7);
;             const bool v0 = tp.sel && (kvc <= tp.lim) && (kvc > tp.lim2), v1 = tp.sel && (kvc + 32 <= tp.lim) && (kvc + 32 > tp.lim2);
;             s0[r] = v0 ? s0[r] : -1e30f; s1[r] = v1 ? s1[r] : -1e30f;
;         }
;     }
;     const float seed = __builtin_fminf(s0[15], s1[15]);
;     float ma = seed, mb = seed;
; #pragma unroll
;     for (int r = 0; r < 16; r += 2) { ma = max3_asm(ma, s0[r], s1[r]); mb = max3_asm(mb, s0[r + 1], s1[r + 1]); }
;     const float mx = fmaxf(ma, mb);
;     return fmaxf(mx, __shfl_xor(mx, 32));
; }
; template <int MODE, bool MASK, bool WITH_O>
; DI void attn_tile_t(lptr Kt, lptr Vt, const bf16x8 (&qf)[4], f32x16& o0, f32x16& o1, RowState& rs, const TP& tp, int lane) {
;     const int hi = lane >> 5;
;     f32x16 s0, s1;
;     bias_init<MODE>(s0, s1, tp, tp.fb - rs.mref, hi);
;     qk_acc(Kt, qf, s0, s1, lane);
;     const float mx = mask_rowmax<MASK>(s0, s1, tp);
;     const bool was = rs.seen; rs.seen = was || (mx > -1e29f);
;     const bool trig = (mx > 8.f) || (!was && mx > -1e29f && mx < -8.f);
;     if (__builtin_expect(__any(trig), 0)) {
; DI void slc_unit(const Params& P, lptr L, int u, int tid, int lane, int wid) {
;     ...
;         const int j = (int)list[jt], kv0 = j * 64;
;         const bool sel = (sm[ql * 8 + (j >> 5)] >> (j & 31)) & 1u;
;         if (__any(sel)) {
;             TP tp; tp.cs = nullptr; tp.sl = sl; tp.fb = sl * (float)(kv0 + 8 * hi - t); tp.lim = t - kv0 - 8 * hi; tp.lim2 = -(1 << 30); tp.sel = sel;
;             attn_tile<1>(Kt, Vt, qf, o0, o1, rs, tp, true, lane);
.LBB0_613:
	v_mov_b32_e32 v0, v253
	s_and_b32 s31, s0, 1
	v_and_b32_e32 v35, 31, v253
	v_lshrrev_b32_e32 v36, v0, v255
	v_bfe_u32 v34, v255, v35, 1
	v_and_b32_e32 v35, 1, v36
	v_cmp_ne_u32_e32 vcc, 0, v34
	v_cmp_eq_u32_e64 s[28:29], 1, v35
	s_cbranch_vccz .LBB0_618
	s_mul_i32 s33, s31, 0x2400
	v_add_u32_e32 v232, s33, v170
	ds_read_b128 v[102:105], v232 offset:4608
	ds_read_b128 v[106:109], v232
	ds_read_b128 v[110:113], v232 offset:32
	ds_read_b128 v[114:117], v232 offset:4640
	ds_read_b128 v[118:121], v232 offset:64
	ds_read_b128 v[158:161], v232 offset:4672
	ds_read_b128 v[162:165], v232 offset:96
	ds_read_b128 v[166:169], v232 offset:4704
	v_lshl_or_b32 v0, v0, 6, v126
	v_sub_u32_e32 v34, v0, v91
	v_cvt_f32_i32_e32 v34, v34
	s_mov_b32 s0, 2.0
	v_sub_u32_e32 v152, v91, v0
	s_mov_b32 s1, 0x40400000
	v_cmp_lt_i32_e32 vcc, 54, v152
	v_fma_f32 v0, v150, v34, -v101
	s_cmp_eq_u64 vcc, exec
	s_cselect_b64 s[98:99], -1, 0
	s_orn2_b64 s[100:101], s[28:29], s[98:99]
	v_cndmask_b32_e64 v0, v210, v0, s[100:101]
	v_pk_fma_f32 v[36:37], v[94:95], s[0:1], v[0:1] op_sel_hi:[1,1,0]
	s_mov_b32 s0, 4.0
	s_mov_b32 s1, 0x40a00000
	v_pk_fma_f32 v[38:39], v[94:95], s[0:1], v[0:1] op_sel_hi:[1,1,0]
	s_mov_b32 s0, 0x40c00000
	s_mov_b32 s1, 0x40e00000
	v_pk_fma_f32 v[40:41], v[94:95], s[0:1], v[0:1] op_sel_hi:[1,1,0]
	s_mov_b32 s0, 0x41800000
	s_mov_b32 s1, 0x41880000
	v_pk_fma_f32 v[42:43], v[94:95], s[0:1], v[0:1] op_sel_hi:[1,1,0]
	s_mov_b32 s0, 0x41900000
	s_mov_b32 s1, 0x41980000
	v_pk_fma_f32 v[44:45], v[94:95], s[0:1], v[0:1] op_sel_hi:[1,1,0]
	s_mov_b32 s0, 0x41a00000
	s_mov_b32 s1, 0x41a80000
	v_mov_b32_e32 v151, v150
	v_fma_f32 v34, 0, v150, v0
	v_add_f32_e32 v35, v150, v0
	v_pk_fma_f32 v[46:47], v[94:95], s[0:1], v[0:1] op_sel_hi:[1,1,0]
	v_pk_fma_f32 v[48:49], v[94:95], s[18:19], v[0:1] op_sel_hi:[1,1,0]
	v_pk_fma_f32 v[64:65], v[150:151], s[4:5], v[0:1] op_sel_hi:[1,1,0]
	v_pk_fma_f32 v[62:63], v[150:151], s[14:15], v[0:1] op_sel_hi:[1,1,0]
	v_pk_fma_f32 v[60:61], v[150:151], s[16:17], v[0:1] op_sel_hi:[1,1,0]
	v_pk_fma_f32 v[58:59], v[150:151], s[94:95], v[0:1] op_sel_hi:[1,1,0]
	v_pk_fma_f32 v[56:57], v[150:151], s[96:97], v[0:1] op_sel_hi:[1,1,0]
	v_pk_fma_f32 v[54:55], v[150:151], s[84:85], v[0:1] op_sel_hi:[1,1,0]
	v_pk_fma_f32 v[52:53], v[150:151], s[72:73], v[0:1] op_sel_hi:[1,1,0]
	v_pk_fma_f32 v[50:51], v[96:97], s[44:45], v[0:1] op_sel_hi:[1,1,0]
	s_setprio 1
	s_waitcnt lgkmcnt(6)
	v_mfma_f32_32x32x16_bf16 v[34:49], v[106:109], v[66:69], v[34:49]
	v_mfma_f32_32x32x16_bf16 v[50:65], v[102:105], v[66:69], v[50:65]
	s_waitcnt lgkmcnt(5)
	v_mfma_f32_32x32x16_bf16 v[34:49], v[110:113], v[70:73], v[34:49]
	s_waitcnt lgkmcnt(4)
	v_mfma_f32_32x32x16_bf16 v[50:65], v[114:117], v[70:73], v[50:65]
	s_waitcnt lgkmcnt(3)
	v_mfma_f32_32x32x16_bf16 v[34:49], v[118:121], v[74:77], v[34:49]
	s_waitcnt lgkmcnt(2)
	v_mfma_f32_32x32x16_bf16 v[50:65], v[158:161], v[74:77], v[50:65]
	s_waitcnt lgkmcnt(1)
	v_mfma_f32_32x32x16_bf16 v[34:49], v[162:165], v[78:81], v[34:49]
	s_waitcnt lgkmcnt(0)
	v_mfma_f32_32x32x16_bf16 v[50:65], v[166:169], v[78:81], v[50:65]
	s_setprio 0
	s_and_b64 vcc, exec, s[98:99]
	s_cbranch_vccz .Lslc_masked
	s_nop 10
	v_max_f32_e32 v252, v65, v65
	v_max_f32_e32 v228, v49, v49
	v_min_f32_e32 v252, v228, v252
	v_max3_f32 v228, v252, v34, v50
	v_max3_f32 v252, v252, v35, v51
	s_mov_b32 s0, 0xefa18f08
	v_max3_f32 v228, v228, v36, v52
	v_max3_f32 v252, v252, v37, v53
	s_nop 0
	v_max3_f32 v228, v228, v38, v54
	v_max3_f32 v252, v252, v39, v55
	s_nop 0
	v_max3_f32 v228, v228, v40, v56
	v_max3_f32 v252, v252, v41, v57
	s_nop 0
	v_max3_f32 v228, v228, v42, v58
	v_max3_f32 v252, v252, v43, v59
	s_nop 0
	v_max3_f32 v228, v228, v44, v60
	v_max3_f32 v252, v252, v45, v61
	s_nop 0
	v_max3_f32 v228, v228, v46, v62
	v_max3_f32 v252, v252, v47, v63
	s_nop 0
	v_max3_f32 v228, v228, v48, v64
	v_max3_f32 v252, v252, v49, v65
	s_nop 0
	v_max_f32_e32 v252, v252, v252
	v_max_f32_e32 v228, v228, v228
	v_max_f32_e32 v252, v228, v252
	v_mov_b32_e32 v228, v252
	s_nop 1
	v_permlane32_swap_b32_e32 v228, v252
	s_waitcnt lgkmcnt(0)
	v_max_f32_e32 v252, v252, v228
	v_cmp_lt_f32_e64 s[28:29], s0, v252
	s_mov_b32 s0, 0x41000000
	v_cmp_lt_f32_e32 vcc, s0, v252
	s_mov_b32 s0, 0xc1000000
	v_cmp_gt_f32_e64 s[0:1], s0, v252
	s_and_b64 s[0:1], s[0:1], s[28:29]
	s_andn2_b64 s[0:1], s[0:1], s[22:23]
	s_or_b64 s[0:1], s[0:1], vcc
	s_and_b64 vcc, exec, s[0:1]
	s_cbranch_vccnz .Lsf_rare
; template <int MODE, bool MASK, bool WITH_O>
; DI void attn_tile_t(lptr Kt, lptr Vt, const bf16x8 (&qf)[4], f32x16& o0, f32x16& o1, RowState& rs, const TP& tp, int lane) {
;     ...
;     } else {
;         const int i = lane & 31;
;         lptr vp = Vt + i * KPB + hi * 16;
;         float sum = 0.f;
;     ...
;         PV_STEP(s0, 0, 0) PV_STEP(s0, 8, 32) PV_STEP(s1, 0, 64) PV_STEP(s1, 8, 96)
;     ...
;         rs.l += sum;
	v_exp_f32_e32 v252, v34
	v_exp_f32_e32 v103, v35
	v_exp_f32_e32 v111, v36
	v_exp_f32_e32 v105, v37
	v_add_f32_e32 v106, 0, v252
	v_add_f32_e32 v106, v103, v106
	v_add_f32_e32 v104, v111, v106
	v_exp_f32_e32 v106, v38
	v_exp_f32_e32 v107, v39
	v_add_u32_e32 v228, s33, v172
	v_exp_f32_e32 v108, v40
	ds_read_b128 v[236:239], v228 offset:18432
	ds_read_b128 v[240:243], v228 offset:23040
	v_add_f32_e32 v104, v105, v104
	v_exp_f32_e32 v109, v41
	v_add_f32_e32 v104, v106, v104
	v_add_f32_e32 v104, v107, v104
	v_add_f32_e32 v104, v108, v104
	v_add_f32_e32 v110, v109, v104
	v_cvt_pk_bf16_f32 v104, v252, v103
	v_cvt_pk_bf16_f32 v105, v111, v105
	v_cvt_pk_bf16_f32 v106, v106, v107
	v_cvt_pk_bf16_f32 v107, v108, v109
	s_or_b64 s[22:23], s[22:23], s[28:29]
	s_waitcnt lgkmcnt(1)
	v_mfma_f32_32x32x16_bf16 v[18:33], v[236:239], v[104:107], v[18:33]
	s_waitcnt lgkmcnt(0)
	v_mfma_f32_32x32x16_bf16 v[2:17], v[240:243], v[104:107], v[2:17]
	v_exp_f32_e32 v252, v42
	v_exp_f32_e32 v43, v43
	v_exp_f32_e32 v103, v44
	v_exp_f32_e32 v44, v45
	v_add_f32_e32 v229, v252, v110
	v_exp_f32_e32 v45, v46
	v_add_f32_e32 v229, v43, v229
	v_exp_f32_e32 v46, v47
	v_add_f32_e32 v42, v103, v229
	v_exp_f32_e32 v47, v48
	ds_read_b128 v[236:239], v228 offset:18464
	ds_read_b128 v[240:243], v228 offset:23072
	v_add_f32_e32 v42, v44, v42
	v_exp_f32_e32 v48, v49
	v_add_f32_e32 v42, v45, v42
	v_add_f32_e32 v42, v46, v42
	v_add_f32_e32 v42, v47, v42
	v_add_f32_e32 v229, v48, v42
	v_cvt_pk_bf16_f32 v42, v252, v43
	v_cvt_pk_bf16_f32 v43, v103, v44
	v_cvt_pk_bf16_f32 v44, v45, v46
	v_cvt_pk_bf16_f32 v45, v47, v48
	s_waitcnt lgkmcnt(1)
	s_nop 0
	v_mfma_f32_32x32x16_bf16 v[18:33], v[236:239], v[42:45], v[18:33]
	s_waitcnt lgkmcnt(0)
	v_mfma_f32_32x32x16_bf16 v[2:17], v[240:243], v[42:45], v[2:17]
	v_exp_f32_e32 v230, v50
	v_exp_f32_e32 v51, v51
	v_exp_f32_e32 v231, v52
	v_exp_f32_e32 v52, v53
	v_add_f32_e32 v229, v230, v229
	v_exp_f32_e32 v53, v54
	v_add_f32_e32 v229, v51, v229
	v_exp_f32_e32 v54, v55
	v_add_f32_e32 v50, v231, v229
	v_exp_f32_e32 v55, v56
	ds_read_b128 v[42:45], v228 offset:18496
	ds_read_b128 v[46:49], v228 offset:23104
	v_add_f32_e32 v50, v52, v50
	v_exp_f32_e32 v41, v57
	v_add_f32_e32 v50, v53, v50
	v_add_f32_e32 v50, v54, v50
	v_add_f32_e32 v50, v55, v50
	v_add_f32_e32 v56, v41, v50
	v_cvt_pk_bf16_f32 v50, v230, v51
	v_cvt_pk_bf16_f32 v51, v231, v52
	v_cvt_pk_bf16_f32 v52, v53, v54
	v_cvt_pk_bf16_f32 v53, v55, v41
	s_waitcnt lgkmcnt(1)
	s_nop 0
	v_mfma_f32_32x32x16_bf16 v[18:33], v[42:45], v[50:53], v[18:33]
	s_waitcnt lgkmcnt(0)
	v_mfma_f32_32x32x16_bf16 v[2:17], v[46:49], v[50:53], v[2:17]
	v_exp_f32_e32 v38, v58
	v_exp_f32_e32 v34, v59
	v_exp_f32_e32 v0, v60
	v_exp_f32_e32 v35, v61
	v_add_f32_e32 v41, v38, v56
	v_exp_f32_e32 v36, v62
	ds_read_b128 v[42:45], v228 offset:18528
	ds_read_b128 v[46:49], v228 offset:23136
	v_add_f32_e32 v41, v34, v41
	v_exp_f32_e32 v37, v63
	v_exp_f32_e32 v39, v64
	v_exp_f32_e32 v40, v65
	v_add_f32_e32 v41, v0, v41
	v_add_f32_e32 v41, v35, v41
	v_add_f32_e32 v41, v36, v41
	v_add_f32_e32 v41, v37, v41
	v_cvt_pk_bf16_f32 v34, v38, v34
	v_cvt_pk_bf16_f32 v35, v0, v35
	v_cvt_pk_bf16_f32 v36, v36, v37
	v_cvt_pk_bf16_f32 v37, v39, v40
	v_add_f32_e32 v41, v39, v41
	v_add_f32_e32 v41, v40, v41
	s_waitcnt lgkmcnt(1)
	v_mfma_f32_32x32x16_bf16 v[18:33], v[42:45], v[34:37], v[18:33]
	s_waitcnt lgkmcnt(0)
	v_mfma_f32_32x32x16_bf16 v[2:17], v[46:49], v[34:37], v[2:17]
	v_add_f32_e32 v100, v100, v41
	s_branch .LBB0_618

; DI void slc_unit(const Params& P, lptr L, int u, int tid, int lane, int wid) {
;     ...
;     ATT_LOOP_BEGIN(NTS, false, kb_ + (size_t)((int)list[jt] * 64) * PROJ_LD, vb_ + (size_t)((int)list[jt]) * 64, (const float*)nullptr)
;         const int j = (int)list[jt], kv0 = j * 64;
;         const bool sel = (sm[ql * 8 + (j >> 5)] >> (j & 31)) & 1u;
.LBB0_620:
	s_andn2_b64 vcc, exec, s[24:25]
	s_waitcnt lgkmcnt(0)
	v_mov_b32_e32 v253, v254
	v_mov_b32_e32 v254, v248
	v_mov_b32_e32 v255, v247
	s_barrier
	s_cbranch_vccz .LBB0_624
	s_mov_b32 s0, s30
	s_branch .LBB0_611
